# EpiNormResNorm step 5: serialized load/compute/store ladder software-pipelined (8 base row loads in flight in a register ring, counted vmcnt), both copies; on top of step-1 LDS-DMA prefetch
# baseline (speedup 1.0000x reference)
; __device__ __forceinline__ unsigned cvt_pk_bf16(float lo, float hi) { unsigned r; asm volatile("v_cvt_pk_bf16_f32 %0, %1, %2" : "=v"(r) : "v"(lo), "v"(hi)); return r; }
;     __device__ __forceinline__ void fused(f32x4 (&acc)[2][2][4][2], const Unit& u, int wr, int wc, int fr, int fq, PG8_LAS unsigned char* lds, int wid, int lane) const {
;     ...
;         f32x4 g2v[2][2];
; #pragma unroll
;         for (int bj = 0; bj < 2; ++bj)
; #pragma unroll
;             for (int n = 0; n < 2; ++n) g2v[bj][n] = *(const f32x4*)(g2 + col0 + bj * HALF + n * 16);
; #pragma unroll
;         for (int ai = 0; ai < 2; ++ai)
; #pragma unroll
;             for (int m = 0; m < 4; ++m) { const int r = ai * HALF + wr * 64 + m * 16 + fr; const f32x2v sr = S[r]; const size_t off = (size_t)(u.pm * BM + r) * 1024 + col0;
; #pragma unroll
;                 for (int bj = 0; bj < 2; ++bj)
; #pragma unroll
;                     for (int n = 0; n < 2; ++n) { const f32x4 bs = *(const f32x4*)(base + off + bj * HALF + n * 16); const f32x4 x1 = bs + acc[ai][bj][m][n] * sr.x * gv[bj][n];
;                         const f32x4 o = x1 * sr.y * g2v[bj][n]; u32x2 w; w.x = cvt_pk_bf16(o[0], o[1]); w.y = cvt_pk_bf16(o[2], o[3]);
;                         if (!dry || x1[0] == 1.2345e38f) { *(f32x4*)(out + off + bj * HALF + n * 16) = x1; *(u32x2*)(xn + off + bj * HALF + n * 16) = w; } }
;                 if (m & 1) asm volatile("" ::: "memory"); }
.LBB0_858:
	s_or_b64 exec, exec, s[6:7]
	v_lshl_add_u64 v[148:149], v[34:35], 2, s[28:29]
	s_mov_b64 s[4:5], 0x2000
	s_waitcnt lgkmcnt(0)
	v_lshl_add_u64 v[150:151], v[148:149], 0, s[4:5]
	v_add_co_u32_e32 v148, vcc, 0x2000, v148
	s_waitcnt lgkmcnt(0)
	s_barrier
	s_nop 0
	v_addc_co_u32_e32 v149, vcc, 0, v149, vcc
	global_load_dwordx4 v[160:163], v[148:149], off
	global_load_dwordx4 v[156:159], v[150:151], off offset:64
	global_load_dwordx4 v[152:155], v[150:151], off offset:512
	s_nop 0
	global_load_dwordx4 v[148:151], v[150:151], off offset:576
	v_lshl_add_u32 v33, v237, 3, 0
	s_add_u32 s6, s22, 0xe300000
	s_addc_u32 s7, s23, 0
	global_load_dwordx4 v[208:211], v[164:165], off
	global_load_dwordx4 v[212:215], v[164:165], off offset:64
	global_load_dwordx4 v[216:219], v[164:165], off offset:512
	global_load_dwordx4 v[220:223], v[164:165], off offset:576
	global_load_dwordx4 v[224:227], v[168:169], off
	global_load_dwordx4 v[238:241], v[168:169], off offset:64
	global_load_dwordx4 v[242:245], v[168:169], off offset:512
	global_load_dwordx4 v[246:249], v[168:169], off offset:576
	ds_read_b64 v[206:207], v33 offset:16384
	v_lshlrev_b64 v[252:253], 10, v[166:167]
	v_lshl_add_u64 v[252:253], v[252:253], 0, v[34:35]
	v_lshl_add_u64 v[250:251], v[252:253], 2, s[20:21]
	v_lshl_add_u64 v[252:253], v[252:253], 1, s[6:7]
	s_waitcnt lgkmcnt(0)
	v_pk_mul_f32 v[144:145], v[144:145], v[206:207] op_sel_hi:[1,0]
	v_pk_mul_f32 v[146:147], v[146:147], v[206:207] op_sel_hi:[1,0]
	v_pk_mul_f32 v[140:141], v[140:141], v[206:207] op_sel_hi:[1,0]
	v_pk_mul_f32 v[142:143], v[142:143], v[206:207] op_sel_hi:[1,0]
	v_pk_mul_f32 v[136:137], v[136:137], v[206:207] op_sel_hi:[1,0]
	v_pk_mul_f32 v[138:139], v[138:139], v[206:207] op_sel_hi:[1,0]
	v_pk_mul_f32 v[132:133], v[132:133], v[206:207] op_sel_hi:[1,0]
	v_pk_mul_f32 v[134:135], v[134:135], v[206:207] op_sel_hi:[1,0]
	s_waitcnt vmcnt(7)
	v_pk_fma_f32 v[144:145], v[116:117], v[144:145], v[208:209]
	v_pk_fma_f32 v[146:147], v[118:119], v[146:147], v[210:211]
	v_pk_mul_f32 v[208:209], v[206:207], v[144:145] op_sel:[1,0]
	v_pk_mul_f32 v[210:211], v[206:207], v[146:147] op_sel:[1,0]
	v_pk_mul_f32 v[208:209], v[160:161], v[208:209]
	v_pk_mul_f32 v[210:211], v[162:163], v[210:211]
	v_cvt_pk_bf16_f32 v208, v208, v209
	v_cvt_pk_bf16_f32 v209, v210, v211
	global_store_dwordx4 v[250:251], v[144:147], off
	global_store_dwordx2 v[252:253], v[208:209], off
	s_waitcnt vmcnt(8)
	v_pk_fma_f32 v[140:141], v[104:105], v[140:141], v[212:213]
	v_pk_fma_f32 v[142:143], v[106:107], v[142:143], v[214:215]
	v_pk_mul_f32 v[212:213], v[206:207], v[140:141] op_sel:[1,0]
	v_pk_mul_f32 v[214:215], v[206:207], v[142:143] op_sel:[1,0]
	v_pk_mul_f32 v[212:213], v[156:157], v[212:213]
	v_pk_mul_f32 v[214:215], v[158:159], v[214:215]
	v_cvt_pk_bf16_f32 v212, v212, v213
	v_cvt_pk_bf16_f32 v213, v214, v215
	global_store_dwordx4 v[250:251], v[140:143], off offset:64
	global_store_dwordx2 v[252:253], v[212:213], off offset:32
	s_waitcnt vmcnt(9)
	v_pk_fma_f32 v[136:137], v[100:101], v[136:137], v[216:217]
	v_pk_fma_f32 v[138:139], v[102:103], v[138:139], v[218:219]
	v_pk_mul_f32 v[216:217], v[206:207], v[136:137] op_sel:[1,0]
	v_pk_mul_f32 v[218:219], v[206:207], v[138:139] op_sel:[1,0]
	v_pk_mul_f32 v[216:217], v[152:153], v[216:217]
	v_pk_mul_f32 v[218:219], v[154:155], v[218:219]
	v_cvt_pk_bf16_f32 v216, v216, v217
	v_cvt_pk_bf16_f32 v217, v218, v219
	global_store_dwordx4 v[250:251], v[136:139], off offset:512
	global_store_dwordx2 v[252:253], v[216:217], off offset:256
	s_waitcnt vmcnt(10)
	v_pk_fma_f32 v[132:133], v[92:93], v[132:133], v[220:221]
	v_pk_fma_f32 v[134:135], v[94:95], v[134:135], v[222:223]
	v_pk_mul_f32 v[220:221], v[206:207], v[132:133] op_sel:[1,0]
	v_pk_mul_f32 v[222:223], v[206:207], v[134:135] op_sel:[1,0]
	v_pk_mul_f32 v[220:221], v[148:149], v[220:221]
	v_pk_mul_f32 v[222:223], v[150:151], v[222:223]
	v_cvt_pk_bf16_f32 v220, v220, v221
	v_cvt_pk_bf16_f32 v221, v222, v223
	global_store_dwordx4 v[250:251], v[132:135], off offset:576
	global_store_dwordx2 v[252:253], v[220:221], off offset:288
	global_load_dwordx4 v[208:211], v[172:173], off
	global_load_dwordx4 v[212:215], v[172:173], off offset:64
	global_load_dwordx4 v[216:219], v[172:173], off offset:512
	global_load_dwordx4 v[220:223], v[172:173], off offset:576
	ds_read_b64 v[206:207], v33 offset:16512
	v_lshlrev_b64 v[252:253], 10, v[170:171]
	v_lshl_add_u64 v[252:253], v[252:253], 0, v[34:35]
	v_lshl_add_u64 v[250:251], v[252:253], 2, s[20:21]
	v_lshl_add_u64 v[252:253], v[252:253], 1, s[6:7]
	s_waitcnt lgkmcnt(0)
	v_pk_mul_f32 v[128:129], v[128:129], v[206:207] op_sel_hi:[1,0]
	v_pk_mul_f32 v[130:131], v[130:131], v[206:207] op_sel_hi:[1,0]
	v_pk_mul_f32 v[124:125], v[124:125], v[206:207] op_sel_hi:[1,0]
	v_pk_mul_f32 v[126:127], v[126:127], v[206:207] op_sel_hi:[1,0]
	v_pk_mul_f32 v[120:121], v[120:121], v[206:207] op_sel_hi:[1,0]
	v_pk_mul_f32 v[122:123], v[122:123], v[206:207] op_sel_hi:[1,0]
	v_pk_mul_f32 v[112:113], v[112:113], v[206:207] op_sel_hi:[1,0]
	v_pk_mul_f32 v[114:115], v[114:115], v[206:207] op_sel_hi:[1,0]
	s_waitcnt vmcnt(15)
	v_pk_fma_f32 v[128:129], v[116:117], v[128:129], v[224:225]
	v_pk_fma_f32 v[130:131], v[118:119], v[130:131], v[226:227]
	v_pk_mul_f32 v[224:225], v[206:207], v[128:129] op_sel:[1,0]
	v_pk_mul_f32 v[226:227], v[206:207], v[130:131] op_sel:[1,0]
	v_pk_mul_f32 v[224:225], v[160:161], v[224:225]
	v_pk_mul_f32 v[226:227], v[162:163], v[226:227]
	v_cvt_pk_bf16_f32 v224, v224, v225
	v_cvt_pk_bf16_f32 v225, v226, v227
	global_store_dwordx4 v[250:251], v[128:131], off
	global_store_dwordx2 v[252:253], v[224:225], off
	s_waitcnt vmcnt(16)
; __device__ __forceinline__ unsigned cvt_pk_bf16(float lo, float hi) { unsigned r; asm volatile("v_cvt_pk_bf16_f32 %0, %1, %2" : "=v"(r) : "v"(lo), "v"(hi)); return r; }
;     __device__ __forceinline__ void fused(f32x4 (&acc)[2][2][4][2], const Unit& u, int wr, int wc, int fr, int fq, PG8_LAS unsigned char* lds, int wid, int lane) const {
;     ...
; #pragma unroll
;         for (int ai = 0; ai < 2; ++ai)
; #pragma unroll
;             for (int m = 0; m < 4; ++m) { const int r = ai * HALF + wr * 64 + m * 16 + fr; const f32x2v sr = S[r]; const size_t off = (size_t)(u.pm * BM + r) * 1024 + col0;
; #pragma unroll
;                 for (int bj = 0; bj < 2; ++bj)
; #pragma unroll
;                     for (int n = 0; n < 2; ++n) { const f32x4 bs = *(const f32x4*)(base + off + bj * HALF + n * 16); const f32x4 x1 = bs + acc[ai][bj][m][n] * sr.x * gv[bj][n];
;                         const f32x4 o = x1 * sr.y * g2v[bj][n]; u32x2 w; w.x = cvt_pk_bf16(o[0], o[1]); w.y = cvt_pk_bf16(o[2], o[3]);
;                         if (!dry || x1[0] == 1.2345e38f) { *(f32x4*)(out + off + bj * HALF + n * 16) = x1; *(u32x2*)(xn + off + bj * HALF + n * 16) = w; } }
;                 if (m & 1) asm volatile("" ::: "memory"); }
	v_pk_fma_f32 v[124:125], v[104:105], v[124:125], v[238:239]
	v_pk_fma_f32 v[126:127], v[106:107], v[126:127], v[240:241]
	v_pk_mul_f32 v[238:239], v[206:207], v[124:125] op_sel:[1,0]
	v_pk_mul_f32 v[240:241], v[206:207], v[126:127] op_sel:[1,0]
	v_pk_mul_f32 v[238:239], v[156:157], v[238:239]
	v_pk_mul_f32 v[240:241], v[158:159], v[240:241]
	v_cvt_pk_bf16_f32 v238, v238, v239
	v_cvt_pk_bf16_f32 v239, v240, v241
	global_store_dwordx4 v[250:251], v[124:127], off offset:64
	global_store_dwordx2 v[252:253], v[238:239], off offset:32
	s_waitcnt vmcnt(17)
	v_pk_fma_f32 v[120:121], v[100:101], v[120:121], v[242:243]
	v_pk_fma_f32 v[122:123], v[102:103], v[122:123], v[244:245]
	v_pk_mul_f32 v[242:243], v[206:207], v[120:121] op_sel:[1,0]
	v_pk_mul_f32 v[244:245], v[206:207], v[122:123] op_sel:[1,0]
	v_pk_mul_f32 v[242:243], v[152:153], v[242:243]
	v_pk_mul_f32 v[244:245], v[154:155], v[244:245]
	v_cvt_pk_bf16_f32 v242, v242, v243
	v_cvt_pk_bf16_f32 v243, v244, v245
	global_store_dwordx4 v[250:251], v[120:123], off offset:512
	global_store_dwordx2 v[252:253], v[242:243], off offset:256
	s_waitcnt vmcnt(18)
	v_pk_fma_f32 v[112:113], v[92:93], v[112:113], v[246:247]
	v_pk_fma_f32 v[114:115], v[94:95], v[114:115], v[248:249]
	v_pk_mul_f32 v[246:247], v[206:207], v[112:113] op_sel:[1,0]
	v_pk_mul_f32 v[248:249], v[206:207], v[114:115] op_sel:[1,0]
	v_pk_mul_f32 v[246:247], v[148:149], v[246:247]
	v_pk_mul_f32 v[248:249], v[150:151], v[248:249]
	v_cvt_pk_bf16_f32 v246, v246, v247
	v_cvt_pk_bf16_f32 v247, v248, v249
	global_store_dwordx4 v[250:251], v[112:115], off offset:576
	global_store_dwordx2 v[252:253], v[246:247], off offset:288
	global_load_dwordx4 v[224:227], v[176:177], off
	global_load_dwordx4 v[238:241], v[176:177], off offset:64
	global_load_dwordx4 v[242:245], v[176:177], off offset:512
	global_load_dwordx4 v[246:249], v[176:177], off offset:576
	ds_read_b64 v[206:207], v33 offset:16640
	v_lshlrev_b64 v[252:253], 10, v[174:175]
	v_lshl_add_u64 v[252:253], v[252:253], 0, v[34:35]
	v_lshl_add_u64 v[250:251], v[252:253], 2, s[20:21]
	v_lshl_add_u64 v[252:253], v[252:253], 1, s[6:7]
	s_waitcnt lgkmcnt(0)
	v_pk_mul_f32 v[108:109], v[108:109], v[206:207] op_sel_hi:[1,0]
	v_pk_mul_f32 v[110:111], v[110:111], v[206:207] op_sel_hi:[1,0]
	v_pk_mul_f32 v[96:97], v[96:97], v[206:207] op_sel_hi:[1,0]
	v_pk_mul_f32 v[98:99], v[98:99], v[206:207] op_sel_hi:[1,0]
	v_pk_mul_f32 v[88:89], v[88:89], v[206:207] op_sel_hi:[1,0]
	v_pk_mul_f32 v[90:91], v[90:91], v[206:207] op_sel_hi:[1,0]
	v_pk_mul_f32 v[84:85], v[84:85], v[206:207] op_sel_hi:[1,0]
	v_pk_mul_f32 v[86:87], v[86:87], v[206:207] op_sel_hi:[1,0]
	s_waitcnt vmcnt(15)
	v_pk_fma_f32 v[108:109], v[116:117], v[108:109], v[208:209]
	v_pk_fma_f32 v[110:111], v[118:119], v[110:111], v[210:211]
	v_pk_mul_f32 v[208:209], v[206:207], v[108:109] op_sel:[1,0]
	v_pk_mul_f32 v[210:211], v[206:207], v[110:111] op_sel:[1,0]
	v_pk_mul_f32 v[208:209], v[160:161], v[208:209]
	v_pk_mul_f32 v[210:211], v[162:163], v[210:211]
	v_cvt_pk_bf16_f32 v208, v208, v209
	v_cvt_pk_bf16_f32 v209, v210, v211
	global_store_dwordx4 v[250:251], v[108:111], off
	global_store_dwordx2 v[252:253], v[208:209], off
	s_waitcnt vmcnt(16)
	v_pk_fma_f32 v[96:97], v[104:105], v[96:97], v[212:213]
	v_pk_fma_f32 v[98:99], v[106:107], v[98:99], v[214:215]
	v_pk_mul_f32 v[212:213], v[206:207], v[96:97] op_sel:[1,0]
	v_pk_mul_f32 v[214:215], v[206:207], v[98:99] op_sel:[1,0]
	v_pk_mul_f32 v[212:213], v[156:157], v[212:213]
	v_pk_mul_f32 v[214:215], v[158:159], v[214:215]
	v_cvt_pk_bf16_f32 v212, v212, v213
	v_cvt_pk_bf16_f32 v213, v214, v215
	global_store_dwordx4 v[250:251], v[96:99], off offset:64
	global_store_dwordx2 v[252:253], v[212:213], off offset:32
	s_waitcnt vmcnt(17)
	v_pk_fma_f32 v[88:89], v[100:101], v[88:89], v[216:217]
	v_pk_fma_f32 v[90:91], v[102:103], v[90:91], v[218:219]
	v_pk_mul_f32 v[216:217], v[206:207], v[88:89] op_sel:[1,0]
	v_pk_mul_f32 v[218:219], v[206:207], v[90:91] op_sel:[1,0]
	v_pk_mul_f32 v[216:217], v[152:153], v[216:217]
	v_pk_mul_f32 v[218:219], v[154:155], v[218:219]
	v_cvt_pk_bf16_f32 v216, v216, v217
	v_cvt_pk_bf16_f32 v217, v218, v219
	global_store_dwordx4 v[250:251], v[88:91], off offset:512
	global_store_dwordx2 v[252:253], v[216:217], off offset:256
	s_waitcnt vmcnt(18)
	v_pk_fma_f32 v[84:85], v[92:93], v[84:85], v[220:221]
	v_pk_fma_f32 v[86:87], v[94:95], v[86:87], v[222:223]
	v_pk_mul_f32 v[220:221], v[206:207], v[84:85] op_sel:[1,0]
	v_pk_mul_f32 v[222:223], v[206:207], v[86:87] op_sel:[1,0]
	v_pk_mul_f32 v[220:221], v[148:149], v[220:221]
	v_pk_mul_f32 v[222:223], v[150:151], v[222:223]
	v_cvt_pk_bf16_f32 v220, v220, v221
	v_cvt_pk_bf16_f32 v221, v222, v223
	global_store_dwordx4 v[250:251], v[84:87], off offset:576
	global_store_dwordx2 v[252:253], v[220:221], off offset:288
	global_load_dwordx4 v[208:211], v[180:181], off
	global_load_dwordx4 v[212:215], v[180:181], off offset:64
	global_load_dwordx4 v[216:219], v[180:181], off offset:512
	global_load_dwordx4 v[220:223], v[180:181], off offset:576
	ds_read_b64 v[206:207], v33 offset:16768
	v_lshlrev_b64 v[252:253], 10, v[178:179]
	v_lshl_add_u64 v[252:253], v[252:253], 0, v[34:35]
	v_lshl_add_u64 v[250:251], v[252:253], 2, s[20:21]
	v_lshl_add_u64 v[252:253], v[252:253], 1, s[6:7]
	s_waitcnt lgkmcnt(0)
	v_pk_mul_f32 v[80:81], v[80:81], v[206:207] op_sel_hi:[1,0]
	v_pk_mul_f32 v[82:83], v[82:83], v[206:207] op_sel_hi:[1,0]
	v_pk_mul_f32 v[76:77], v[76:77], v[206:207] op_sel_hi:[1,0]
	v_pk_mul_f32 v[78:79], v[78:79], v[206:207] op_sel_hi:[1,0]
	v_pk_mul_f32 v[72:73], v[72:73], v[206:207] op_sel_hi:[1,0]
	v_pk_mul_f32 v[74:75], v[74:75], v[206:207] op_sel_hi:[1,0]
	v_pk_mul_f32 v[68:69], v[68:69], v[206:207] op_sel_hi:[1,0]
	v_pk_mul_f32 v[70:71], v[70:71], v[206:207] op_sel_hi:[1,0]
	s_waitcnt vmcnt(15)
; __device__ __forceinline__ unsigned cvt_pk_bf16(float lo, float hi) { unsigned r; asm volatile("v_cvt_pk_bf16_f32 %0, %1, %2" : "=v"(r) : "v"(lo), "v"(hi)); return r; }
;     __device__ __forceinline__ void fused(f32x4 (&acc)[2][2][4][2], const Unit& u, int wr, int wc, int fr, int fq, PG8_LAS unsigned char* lds, int wid, int lane) const {
;     ...
; #pragma unroll
;         for (int ai = 0; ai < 2; ++ai)
; #pragma unroll
;             for (int m = 0; m < 4; ++m) { const int r = ai * HALF + wr * 64 + m * 16 + fr; const f32x2v sr = S[r]; const size_t off = (size_t)(u.pm * BM + r) * 1024 + col0;
; #pragma unroll
;                 for (int bj = 0; bj < 2; ++bj)
; #pragma unroll
;                     for (int n = 0; n < 2; ++n) { const f32x4 bs = *(const f32x4*)(base + off + bj * HALF + n * 16); const f32x4 x1 = bs + acc[ai][bj][m][n] * sr.x * gv[bj][n];
;                         const f32x4 o = x1 * sr.y * g2v[bj][n]; u32x2 w; w.x = cvt_pk_bf16(o[0], o[1]); w.y = cvt_pk_bf16(o[2], o[3]);
;                         if (!dry || x1[0] == 1.2345e38f) { *(f32x4*)(out + off + bj * HALF + n * 16) = x1; *(u32x2*)(xn + off + bj * HALF + n * 16) = w; } }
;                 if (m & 1) asm volatile("" ::: "memory"); }
	v_pk_fma_f32 v[80:81], v[116:117], v[80:81], v[224:225]
	v_pk_fma_f32 v[82:83], v[118:119], v[82:83], v[226:227]
	v_pk_mul_f32 v[224:225], v[206:207], v[80:81] op_sel:[1,0]
	v_pk_mul_f32 v[226:227], v[206:207], v[82:83] op_sel:[1,0]
	v_pk_mul_f32 v[224:225], v[160:161], v[224:225]
	v_pk_mul_f32 v[226:227], v[162:163], v[226:227]
	v_cvt_pk_bf16_f32 v224, v224, v225
	v_cvt_pk_bf16_f32 v225, v226, v227
	global_store_dwordx4 v[250:251], v[80:83], off
	global_store_dwordx2 v[252:253], v[224:225], off
	s_waitcnt vmcnt(16)
	v_pk_fma_f32 v[76:77], v[104:105], v[76:77], v[238:239]
	v_pk_fma_f32 v[78:79], v[106:107], v[78:79], v[240:241]
	v_pk_mul_f32 v[238:239], v[206:207], v[76:77] op_sel:[1,0]
	v_pk_mul_f32 v[240:241], v[206:207], v[78:79] op_sel:[1,0]
	v_pk_mul_f32 v[238:239], v[156:157], v[238:239]
	v_pk_mul_f32 v[240:241], v[158:159], v[240:241]
	v_cvt_pk_bf16_f32 v238, v238, v239
	v_cvt_pk_bf16_f32 v239, v240, v241
	global_store_dwordx4 v[250:251], v[76:79], off offset:64
	global_store_dwordx2 v[252:253], v[238:239], off offset:32
	s_waitcnt vmcnt(17)
	v_pk_fma_f32 v[72:73], v[100:101], v[72:73], v[242:243]
	v_pk_fma_f32 v[74:75], v[102:103], v[74:75], v[244:245]
	v_pk_mul_f32 v[242:243], v[206:207], v[72:73] op_sel:[1,0]
	v_pk_mul_f32 v[244:245], v[206:207], v[74:75] op_sel:[1,0]
	v_pk_mul_f32 v[242:243], v[152:153], v[242:243]
	v_pk_mul_f32 v[244:245], v[154:155], v[244:245]
	v_cvt_pk_bf16_f32 v242, v242, v243
	v_cvt_pk_bf16_f32 v243, v244, v245
	global_store_dwordx4 v[250:251], v[72:75], off offset:512
	global_store_dwordx2 v[252:253], v[242:243], off offset:256
	s_waitcnt vmcnt(18)
	v_pk_fma_f32 v[68:69], v[92:93], v[68:69], v[246:247]
	v_pk_fma_f32 v[70:71], v[94:95], v[70:71], v[248:249]
	v_pk_mul_f32 v[246:247], v[206:207], v[68:69] op_sel:[1,0]
	v_pk_mul_f32 v[248:249], v[206:207], v[70:71] op_sel:[1,0]
	v_pk_mul_f32 v[246:247], v[148:149], v[246:247]
	v_pk_mul_f32 v[248:249], v[150:151], v[248:249]
	v_cvt_pk_bf16_f32 v246, v246, v247
	v_cvt_pk_bf16_f32 v247, v248, v249
	global_store_dwordx4 v[250:251], v[68:71], off offset:576
	global_store_dwordx2 v[252:253], v[246:247], off offset:288
	global_load_dwordx4 v[224:227], v[184:185], off
	global_load_dwordx4 v[238:241], v[184:185], off offset:64
	global_load_dwordx4 v[242:245], v[184:185], off offset:512
	global_load_dwordx4 v[246:249], v[184:185], off offset:576
	ds_read_b64 v[206:207], v33 offset:17408
	v_lshlrev_b64 v[252:253], 10, v[182:183]
	v_lshl_add_u64 v[252:253], v[252:253], 0, v[34:35]
	v_lshl_add_u64 v[250:251], v[252:253], 2, s[20:21]
	v_lshl_add_u64 v[252:253], v[252:253], 1, s[6:7]
	s_waitcnt lgkmcnt(0)
	v_pk_mul_f32 v[64:65], v[64:65], v[206:207] op_sel_hi:[1,0]
	v_pk_mul_f32 v[66:67], v[66:67], v[206:207] op_sel_hi:[1,0]
	v_pk_mul_f32 v[60:61], v[60:61], v[206:207] op_sel_hi:[1,0]
	v_pk_mul_f32 v[62:63], v[62:63], v[206:207] op_sel_hi:[1,0]
	v_pk_mul_f32 v[56:57], v[56:57], v[206:207] op_sel_hi:[1,0]
	v_pk_mul_f32 v[58:59], v[58:59], v[206:207] op_sel_hi:[1,0]
	v_pk_mul_f32 v[52:53], v[52:53], v[206:207] op_sel_hi:[1,0]
	v_pk_mul_f32 v[54:55], v[54:55], v[206:207] op_sel_hi:[1,0]
	s_waitcnt vmcnt(15)
	v_pk_fma_f32 v[64:65], v[116:117], v[64:65], v[208:209]
	v_pk_fma_f32 v[66:67], v[118:119], v[66:67], v[210:211]
	v_pk_mul_f32 v[208:209], v[206:207], v[64:65] op_sel:[1,0]
	v_pk_mul_f32 v[210:211], v[206:207], v[66:67] op_sel:[1,0]
	v_pk_mul_f32 v[208:209], v[160:161], v[208:209]
	v_pk_mul_f32 v[210:211], v[162:163], v[210:211]
	v_cvt_pk_bf16_f32 v208, v208, v209
	v_cvt_pk_bf16_f32 v209, v210, v211
	global_store_dwordx4 v[250:251], v[64:67], off
	global_store_dwordx2 v[252:253], v[208:209], off
	s_waitcnt vmcnt(16)
	v_pk_fma_f32 v[60:61], v[104:105], v[60:61], v[212:213]
	v_pk_fma_f32 v[62:63], v[106:107], v[62:63], v[214:215]
	v_pk_mul_f32 v[212:213], v[206:207], v[60:61] op_sel:[1,0]
	v_pk_mul_f32 v[214:215], v[206:207], v[62:63] op_sel:[1,0]
	v_pk_mul_f32 v[212:213], v[156:157], v[212:213]
	v_pk_mul_f32 v[214:215], v[158:159], v[214:215]
	v_cvt_pk_bf16_f32 v212, v212, v213
	v_cvt_pk_bf16_f32 v213, v214, v215
	global_store_dwordx4 v[250:251], v[60:63], off offset:64
	global_store_dwordx2 v[252:253], v[212:213], off offset:32
	s_waitcnt vmcnt(17)
	v_pk_fma_f32 v[56:57], v[100:101], v[56:57], v[216:217]
	v_pk_fma_f32 v[58:59], v[102:103], v[58:59], v[218:219]
	v_pk_mul_f32 v[216:217], v[206:207], v[56:57] op_sel:[1,0]
	v_pk_mul_f32 v[218:219], v[206:207], v[58:59] op_sel:[1,0]
	v_pk_mul_f32 v[216:217], v[152:153], v[216:217]
	v_pk_mul_f32 v[218:219], v[154:155], v[218:219]
	v_cvt_pk_bf16_f32 v216, v216, v217
	v_cvt_pk_bf16_f32 v217, v218, v219
	global_store_dwordx4 v[250:251], v[56:59], off offset:512
	global_store_dwordx2 v[252:253], v[216:217], off offset:256
	s_waitcnt vmcnt(18)
	v_pk_fma_f32 v[52:53], v[92:93], v[52:53], v[220:221]
	v_pk_fma_f32 v[54:55], v[94:95], v[54:55], v[222:223]
	v_pk_mul_f32 v[220:221], v[206:207], v[52:53] op_sel:[1,0]
	v_pk_mul_f32 v[222:223], v[206:207], v[54:55] op_sel:[1,0]
	v_pk_mul_f32 v[220:221], v[148:149], v[220:221]
	v_pk_mul_f32 v[222:223], v[150:151], v[222:223]
	v_cvt_pk_bf16_f32 v220, v220, v221
	v_cvt_pk_bf16_f32 v221, v222, v223
	global_store_dwordx4 v[250:251], v[52:55], off offset:576
	global_store_dwordx2 v[252:253], v[220:221], off offset:288
	global_load_dwordx4 v[208:211], v[188:189], off
	global_load_dwordx4 v[212:215], v[188:189], off offset:64
	global_load_dwordx4 v[216:219], v[188:189], off offset:512
	global_load_dwordx4 v[220:223], v[188:189], off offset:576
	ds_read_b64 v[206:207], v33 offset:17536
	v_lshlrev_b64 v[252:253], 10, v[186:187]
	v_lshl_add_u64 v[252:253], v[252:253], 0, v[34:35]
	v_lshl_add_u64 v[250:251], v[252:253], 2, s[20:21]
	v_lshl_add_u64 v[252:253], v[252:253], 1, s[6:7]
	s_waitcnt lgkmcnt(0)
; __device__ __forceinline__ unsigned cvt_pk_bf16(float lo, float hi) { unsigned r; asm volatile("v_cvt_pk_bf16_f32 %0, %1, %2" : "=v"(r) : "v"(lo), "v"(hi)); return r; }
;     __device__ __forceinline__ void fused(f32x4 (&acc)[2][2][4][2], const Unit& u, int wr, int wc, int fr, int fq, PG8_LAS unsigned char* lds, int wid, int lane) const {
;     ...
; #pragma unroll
;         for (int ai = 0; ai < 2; ++ai)
; #pragma unroll
;             for (int m = 0; m < 4; ++m) { const int r = ai * HALF + wr * 64 + m * 16 + fr; const f32x2v sr = S[r]; const size_t off = (size_t)(u.pm * BM + r) * 1024 + col0;
; #pragma unroll
;                 for (int bj = 0; bj < 2; ++bj)
; #pragma unroll
;                     for (int n = 0; n < 2; ++n) { const f32x4 bs = *(const f32x4*)(base + off + bj * HALF + n * 16); const f32x4 x1 = bs + acc[ai][bj][m][n] * sr.x * gv[bj][n];
;                         const f32x4 o = x1 * sr.y * g2v[bj][n]; u32x2 w; w.x = cvt_pk_bf16(o[0], o[1]); w.y = cvt_pk_bf16(o[2], o[3]);
;                         if (!dry || x1[0] == 1.2345e38f) { *(f32x4*)(out + off + bj * HALF + n * 16) = x1; *(u32x2*)(xn + off + bj * HALF + n * 16) = w; } }
;                 if (m & 1) asm volatile("" ::: "memory"); }
	v_pk_mul_f32 v[48:49], v[48:49], v[206:207] op_sel_hi:[1,0]
	v_pk_mul_f32 v[50:51], v[50:51], v[206:207] op_sel_hi:[1,0]
	v_pk_mul_f32 v[44:45], v[44:45], v[206:207] op_sel_hi:[1,0]
	v_pk_mul_f32 v[46:47], v[46:47], v[206:207] op_sel_hi:[1,0]
	v_pk_mul_f32 v[40:41], v[40:41], v[206:207] op_sel_hi:[1,0]
	v_pk_mul_f32 v[42:43], v[42:43], v[206:207] op_sel_hi:[1,0]
	v_pk_mul_f32 v[36:37], v[36:37], v[206:207] op_sel_hi:[1,0]
	v_pk_mul_f32 v[38:39], v[38:39], v[206:207] op_sel_hi:[1,0]
	s_waitcnt vmcnt(15)
	v_pk_fma_f32 v[48:49], v[116:117], v[48:49], v[224:225]
	v_pk_fma_f32 v[50:51], v[118:119], v[50:51], v[226:227]
	v_pk_mul_f32 v[224:225], v[206:207], v[48:49] op_sel:[1,0]
	v_pk_mul_f32 v[226:227], v[206:207], v[50:51] op_sel:[1,0]
	v_pk_mul_f32 v[224:225], v[160:161], v[224:225]
	v_pk_mul_f32 v[226:227], v[162:163], v[226:227]
	v_cvt_pk_bf16_f32 v224, v224, v225
	v_cvt_pk_bf16_f32 v225, v226, v227
	global_store_dwordx4 v[250:251], v[48:51], off
	global_store_dwordx2 v[252:253], v[224:225], off
	s_waitcnt vmcnt(16)
	v_pk_fma_f32 v[44:45], v[104:105], v[44:45], v[238:239]
	v_pk_fma_f32 v[46:47], v[106:107], v[46:47], v[240:241]
	v_pk_mul_f32 v[238:239], v[206:207], v[44:45] op_sel:[1,0]
	v_pk_mul_f32 v[240:241], v[206:207], v[46:47] op_sel:[1,0]
	v_pk_mul_f32 v[238:239], v[156:157], v[238:239]
	v_pk_mul_f32 v[240:241], v[158:159], v[240:241]
	v_cvt_pk_bf16_f32 v238, v238, v239
	v_cvt_pk_bf16_f32 v239, v240, v241
	global_store_dwordx4 v[250:251], v[44:47], off offset:64
	global_store_dwordx2 v[252:253], v[238:239], off offset:32
	s_waitcnt vmcnt(17)
	v_pk_fma_f32 v[40:41], v[100:101], v[40:41], v[242:243]
	v_pk_fma_f32 v[42:43], v[102:103], v[42:43], v[244:245]
	v_pk_mul_f32 v[242:243], v[206:207], v[40:41] op_sel:[1,0]
	v_pk_mul_f32 v[244:245], v[206:207], v[42:43] op_sel:[1,0]
	v_pk_mul_f32 v[242:243], v[152:153], v[242:243]
	v_pk_mul_f32 v[244:245], v[154:155], v[244:245]
	v_cvt_pk_bf16_f32 v242, v242, v243
	v_cvt_pk_bf16_f32 v243, v244, v245
	global_store_dwordx4 v[250:251], v[40:43], off offset:512
	global_store_dwordx2 v[252:253], v[242:243], off offset:256
	s_waitcnt vmcnt(18)
	v_pk_fma_f32 v[36:37], v[92:93], v[36:37], v[246:247]
	v_pk_fma_f32 v[38:39], v[94:95], v[38:39], v[248:249]
	v_pk_mul_f32 v[246:247], v[206:207], v[36:37] op_sel:[1,0]
	v_pk_mul_f32 v[248:249], v[206:207], v[38:39] op_sel:[1,0]
	v_pk_mul_f32 v[246:247], v[148:149], v[246:247]
	v_pk_mul_f32 v[248:249], v[150:151], v[248:249]
	v_cvt_pk_bf16_f32 v246, v246, v247
	v_cvt_pk_bf16_f32 v247, v248, v249
	global_store_dwordx4 v[250:251], v[36:39], off offset:576
	global_store_dwordx2 v[252:253], v[246:247], off offset:288
	global_load_dwordx4 v[224:227], v[192:193], off
	global_load_dwordx4 v[238:241], v[192:193], off offset:64
	global_load_dwordx4 v[242:245], v[192:193], off offset:512
	global_load_dwordx4 v[246:249], v[192:193], off offset:576
	ds_read_b64 v[206:207], v33 offset:17664
	v_lshlrev_b64 v[252:253], 10, v[190:191]
	v_lshl_add_u64 v[252:253], v[252:253], 0, v[34:35]
	v_lshl_add_u64 v[250:251], v[252:253], 2, s[20:21]
	v_lshl_add_u64 v[252:253], v[252:253], 1, s[6:7]
	s_waitcnt lgkmcnt(0)
	v_pk_mul_f32 v[28:29], v[28:29], v[206:207] op_sel_hi:[1,0]
	v_pk_mul_f32 v[30:31], v[30:31], v[206:207] op_sel_hi:[1,0]
	v_pk_mul_f32 v[24:25], v[24:25], v[206:207] op_sel_hi:[1,0]
	v_pk_mul_f32 v[26:27], v[26:27], v[206:207] op_sel_hi:[1,0]
	v_pk_mul_f32 v[20:21], v[20:21], v[206:207] op_sel_hi:[1,0]
	v_pk_mul_f32 v[22:23], v[22:23], v[206:207] op_sel_hi:[1,0]
	v_pk_mul_f32 v[16:17], v[16:17], v[206:207] op_sel_hi:[1,0]
	v_pk_mul_f32 v[18:19], v[18:19], v[206:207] op_sel_hi:[1,0]
	s_waitcnt vmcnt(15)
	v_pk_fma_f32 v[28:29], v[116:117], v[28:29], v[208:209]
	v_pk_fma_f32 v[30:31], v[118:119], v[30:31], v[210:211]
	v_pk_mul_f32 v[208:209], v[206:207], v[28:29] op_sel:[1,0]
	v_pk_mul_f32 v[210:211], v[206:207], v[30:31] op_sel:[1,0]
	v_pk_mul_f32 v[208:209], v[160:161], v[208:209]
	v_pk_mul_f32 v[210:211], v[162:163], v[210:211]
	v_cvt_pk_bf16_f32 v208, v208, v209
	v_cvt_pk_bf16_f32 v209, v210, v211
	global_store_dwordx4 v[250:251], v[28:31], off
	global_store_dwordx2 v[252:253], v[208:209], off
	s_waitcnt vmcnt(16)
; __device__ __forceinline__ unsigned cvt_pk_bf16(float lo, float hi) { unsigned r; asm volatile("v_cvt_pk_bf16_f32 %0, %1, %2" : "=v"(r) : "v"(lo), "v"(hi)); return r; }
;     __device__ __forceinline__ void fused(f32x4 (&acc)[2][2][4][2], const Unit& u, int wr, int wc, int fr, int fq, PG8_LAS unsigned char* lds, int wid, int lane) const {
;     ...
; #pragma unroll
;         for (int ai = 0; ai < 2; ++ai)
; #pragma unroll
;             for (int m = 0; m < 4; ++m) { const int r = ai * HALF + wr * 64 + m * 16 + fr; const f32x2v sr = S[r]; const size_t off = (size_t)(u.pm * BM + r) * 1024 + col0;
; #pragma unroll
;                 for (int bj = 0; bj < 2; ++bj)
; #pragma unroll
;                     for (int n = 0; n < 2; ++n) { const f32x4 bs = *(const f32x4*)(base + off + bj * HALF + n * 16); const f32x4 x1 = bs + acc[ai][bj][m][n] * sr.x * gv[bj][n];
;                         const f32x4 o = x1 * sr.y * g2v[bj][n]; u32x2 w; w.x = cvt_pk_bf16(o[0], o[1]); w.y = cvt_pk_bf16(o[2], o[3]);
;                         if (!dry || x1[0] == 1.2345e38f) { *(f32x4*)(out + off + bj * HALF + n * 16) = x1; *(u32x2*)(xn + off + bj * HALF + n * 16) = w; } }
;                 if (m & 1) asm volatile("" ::: "memory"); }
	v_pk_fma_f32 v[24:25], v[104:105], v[24:25], v[212:213]
	v_pk_fma_f32 v[26:27], v[106:107], v[26:27], v[214:215]
	v_pk_mul_f32 v[212:213], v[206:207], v[24:25] op_sel:[1,0]
	v_pk_mul_f32 v[214:215], v[206:207], v[26:27] op_sel:[1,0]
	v_pk_mul_f32 v[212:213], v[156:157], v[212:213]
	v_pk_mul_f32 v[214:215], v[158:159], v[214:215]
	v_cvt_pk_bf16_f32 v212, v212, v213
	v_cvt_pk_bf16_f32 v213, v214, v215
	global_store_dwordx4 v[250:251], v[24:27], off offset:64
	global_store_dwordx2 v[252:253], v[212:213], off offset:32
	s_waitcnt vmcnt(17)
	v_pk_fma_f32 v[20:21], v[100:101], v[20:21], v[216:217]
	v_pk_fma_f32 v[22:23], v[102:103], v[22:23], v[218:219]
	v_pk_mul_f32 v[216:217], v[206:207], v[20:21] op_sel:[1,0]
	v_pk_mul_f32 v[218:219], v[206:207], v[22:23] op_sel:[1,0]
	v_pk_mul_f32 v[216:217], v[152:153], v[216:217]
	v_pk_mul_f32 v[218:219], v[154:155], v[218:219]
	v_cvt_pk_bf16_f32 v216, v216, v217
	v_cvt_pk_bf16_f32 v217, v218, v219
	global_store_dwordx4 v[250:251], v[20:23], off offset:512
	global_store_dwordx2 v[252:253], v[216:217], off offset:256
	s_waitcnt vmcnt(18)
	v_pk_fma_f32 v[16:17], v[92:93], v[16:17], v[220:221]
	v_pk_fma_f32 v[18:19], v[94:95], v[18:19], v[222:223]
	v_pk_mul_f32 v[220:221], v[206:207], v[16:17] op_sel:[1,0]
	v_pk_mul_f32 v[222:223], v[206:207], v[18:19] op_sel:[1,0]
	v_pk_mul_f32 v[220:221], v[148:149], v[220:221]
	v_pk_mul_f32 v[222:223], v[150:151], v[222:223]
	v_cvt_pk_bf16_f32 v220, v220, v221
	v_cvt_pk_bf16_f32 v221, v222, v223
	global_store_dwordx4 v[250:251], v[16:19], off offset:576
	global_store_dwordx2 v[252:253], v[220:221], off offset:288
	ds_read_b64 v[206:207], v33 offset:17792
	v_lshlrev_b64 v[252:253], 10, v[204:205]
	v_lshl_add_u64 v[252:253], v[252:253], 0, v[34:35]
	v_lshl_add_u64 v[250:251], v[252:253], 2, s[20:21]
	v_lshl_add_u64 v[252:253], v[252:253], 1, s[6:7]
	s_waitcnt lgkmcnt(0)
	v_pk_mul_f32 v[12:13], v[12:13], v[206:207] op_sel_hi:[1,0]
	v_pk_mul_f32 v[14:15], v[14:15], v[206:207] op_sel_hi:[1,0]
	v_pk_mul_f32 v[8:9], v[8:9], v[206:207] op_sel_hi:[1,0]
	v_pk_mul_f32 v[10:11], v[10:11], v[206:207] op_sel_hi:[1,0]
	v_pk_mul_f32 v[4:5], v[4:5], v[206:207] op_sel_hi:[1,0]
	v_pk_mul_f32 v[6:7], v[6:7], v[206:207] op_sel_hi:[1,0]
	v_pk_mul_f32 v[0:1], v[0:1], v[206:207] op_sel_hi:[1,0]
	v_pk_mul_f32 v[2:3], v[2:3], v[206:207] op_sel_hi:[1,0]
	s_waitcnt vmcnt(11)
	v_pk_fma_f32 v[12:13], v[116:117], v[12:13], v[224:225]
	v_pk_fma_f32 v[14:15], v[118:119], v[14:15], v[226:227]
	v_pk_mul_f32 v[224:225], v[206:207], v[12:13] op_sel:[1,0]
	v_pk_mul_f32 v[226:227], v[206:207], v[14:15] op_sel:[1,0]
	v_pk_mul_f32 v[224:225], v[160:161], v[224:225]
	v_pk_mul_f32 v[226:227], v[162:163], v[226:227]
	v_cvt_pk_bf16_f32 v224, v224, v225
	v_cvt_pk_bf16_f32 v225, v226, v227
	global_store_dwordx4 v[250:251], v[12:15], off
	global_store_dwordx2 v[252:253], v[224:225], off
	s_waitcnt vmcnt(12)
	v_pk_fma_f32 v[8:9], v[104:105], v[8:9], v[238:239]
	v_pk_fma_f32 v[10:11], v[106:107], v[10:11], v[240:241]
	v_pk_mul_f32 v[238:239], v[206:207], v[8:9] op_sel:[1,0]
	v_pk_mul_f32 v[240:241], v[206:207], v[10:11] op_sel:[1,0]
	v_pk_mul_f32 v[238:239], v[156:157], v[238:239]
	v_pk_mul_f32 v[240:241], v[158:159], v[240:241]
	v_cvt_pk_bf16_f32 v238, v238, v239
	v_cvt_pk_bf16_f32 v239, v240, v241
	global_store_dwordx4 v[250:251], v[8:11], off offset:64
	global_store_dwordx2 v[252:253], v[238:239], off offset:32
	s_waitcnt vmcnt(13)
	v_pk_fma_f32 v[4:5], v[100:101], v[4:5], v[242:243]
	v_pk_fma_f32 v[6:7], v[102:103], v[6:7], v[244:245]
	v_pk_mul_f32 v[242:243], v[206:207], v[4:5] op_sel:[1,0]
	v_pk_mul_f32 v[244:245], v[206:207], v[6:7] op_sel:[1,0]
	v_pk_mul_f32 v[242:243], v[152:153], v[242:243]
	v_pk_mul_f32 v[244:245], v[154:155], v[244:245]
	v_cvt_pk_bf16_f32 v242, v242, v243
	v_cvt_pk_bf16_f32 v243, v244, v245
	global_store_dwordx4 v[250:251], v[4:7], off offset:512
	global_store_dwordx2 v[252:253], v[242:243], off offset:256
	s_waitcnt vmcnt(14)
	v_pk_fma_f32 v[0:1], v[92:93], v[0:1], v[246:247]
	v_pk_fma_f32 v[2:3], v[94:95], v[2:3], v[248:249]
	v_pk_mul_f32 v[246:247], v[206:207], v[0:1] op_sel:[1,0]
	v_pk_mul_f32 v[248:249], v[206:207], v[2:3] op_sel:[1,0]
	v_pk_mul_f32 v[246:247], v[148:149], v[246:247]
	v_pk_mul_f32 v[248:249], v[150:151], v[248:249]
	v_cvt_pk_bf16_f32 v246, v246, v247
	v_cvt_pk_bf16_f32 v247, v248, v249
	global_store_dwordx4 v[250:251], v[0:3], off offset:576
	global_store_dwordx2 v[252:253], v[246:247], off offset:288

; __device__ __forceinline__ unsigned cvt_pk_bf16(float lo, float hi) { unsigned r; asm volatile("v_cvt_pk_bf16_f32 %0, %1, %2" : "=v"(r) : "v"(lo), "v"(hi)); return r; }
;     __device__ __forceinline__ void fused(f32x4 (&acc)[2][2][4][2], const Unit& u, int wr, int wc, int fr, int fq, PG8_LAS unsigned char* lds, int wid, int lane) const {
;     ...
;         f32x4 g2v[2][2];
; #pragma unroll
;         for (int bj = 0; bj < 2; ++bj)
; #pragma unroll
;             for (int n = 0; n < 2; ++n) g2v[bj][n] = *(const f32x4*)(g2 + col0 + bj * HALF + n * 16);
; #pragma unroll
;         for (int ai = 0; ai < 2; ++ai)
; #pragma unroll
;             for (int m = 0; m < 4; ++m) { const int r = ai * HALF + wr * 64 + m * 16 + fr; const f32x2v sr = S[r]; const size_t off = (size_t)(u.pm * BM + r) * 1024 + col0;
; #pragma unroll
;                 for (int bj = 0; bj < 2; ++bj)
; #pragma unroll
;                     for (int n = 0; n < 2; ++n) { const f32x4 bs = *(const f32x4*)(base + off + bj * HALF + n * 16); const f32x4 x1 = bs + acc[ai][bj][m][n] * sr.x * gv[bj][n];
;                         const f32x4 o = x1 * sr.y * g2v[bj][n]; u32x2 w; w.x = cvt_pk_bf16(o[0], o[1]); w.y = cvt_pk_bf16(o[2], o[3]);
;                         if (!dry || x1[0] == 1.2345e38f) { *(f32x4*)(out + off + bj * HALF + n * 16) = x1; *(u32x2*)(xn + off + bj * HALF + n * 16) = w; } }
;                 if (m & 1) asm volatile("" ::: "memory"); }
.LBB0_1115:
	s_or_b64 exec, exec, s[6:7]
	s_ashr_i32 s19, s18, 31
	s_lshl_b64 s[4:5], s[18:19], 14
	s_add_u32 s6, s26, s4
	s_addc_u32 s7, s27, s5
	s_and_b64 s[4:5], s[22:23], exec
	s_cselect_b32 s4, s7, s43
	s_cselect_b32 s5, s6, s42
	s_waitcnt lgkmcnt(0)
	s_barrier
	v_mov_b32_e32 v206, s5
	v_mov_b32_e32 v207, s4
	v_lshl_add_u64 v[206:207], v[34:35], 2, v[206:207]
	global_load_dwordx4 v[148:151], v[206:207], off
	global_load_dwordx4 v[152:155], v[206:207], off offset:64
	global_load_dwordx4 v[156:159], v[206:207], off offset:512
	global_load_dwordx4 v[160:163], v[206:207], off offset:576
	v_lshl_add_u32 v33, v237, 3, 0
	s_add_u32 s6, s24, 0xe300000
	s_addc_u32 s7, s25, 0
	global_load_dwordx4 v[208:211], v[164:165], off
	global_load_dwordx4 v[212:215], v[164:165], off offset:64
	global_load_dwordx4 v[216:219], v[164:165], off offset:512
	global_load_dwordx4 v[220:223], v[164:165], off offset:576
	global_load_dwordx4 v[224:227], v[168:169], off
	global_load_dwordx4 v[238:241], v[168:169], off offset:64
	global_load_dwordx4 v[242:245], v[168:169], off offset:512
	global_load_dwordx4 v[246:249], v[168:169], off offset:576
	ds_read_b64 v[206:207], v33 offset:16384
	v_lshlrev_b64 v[252:253], 10, v[166:167]
	v_lshl_add_u64 v[252:253], v[252:253], 0, v[34:35]
	v_lshl_add_u64 v[252:253], v[252:253], 1, s[6:7]
	s_waitcnt lgkmcnt(0)
	v_pk_mul_f32 v[128:129], v[128:129], v[206:207] op_sel_hi:[1,0]
	v_pk_mul_f32 v[130:131], v[130:131], v[206:207] op_sel_hi:[1,0]
	v_pk_mul_f32 v[124:125], v[124:125], v[206:207] op_sel_hi:[1,0]
	v_pk_mul_f32 v[126:127], v[126:127], v[206:207] op_sel_hi:[1,0]
	v_pk_mul_f32 v[120:121], v[120:121], v[206:207] op_sel_hi:[1,0]
	v_pk_mul_f32 v[122:123], v[122:123], v[206:207] op_sel_hi:[1,0]
	v_pk_mul_f32 v[116:117], v[116:117], v[206:207] op_sel_hi:[1,0]
	v_pk_mul_f32 v[118:119], v[118:119], v[206:207] op_sel_hi:[1,0]
	s_waitcnt vmcnt(7)
	v_pk_fma_f32 v[128:129], v[144:145], v[128:129], v[208:209]
	v_pk_fma_f32 v[130:131], v[146:147], v[130:131], v[210:211]
	v_pk_mul_f32 v[208:209], v[206:207], v[128:129] op_sel:[1,0]
	v_pk_mul_f32 v[210:211], v[206:207], v[130:131] op_sel:[1,0]
	v_pk_mul_f32 v[208:209], v[148:149], v[208:209]
	v_pk_mul_f32 v[210:211], v[150:151], v[210:211]
	v_cvt_pk_bf16_f32 v208, v208, v209
	v_cvt_pk_bf16_f32 v209, v210, v211
	global_store_dwordx4 v[164:165], v[128:131], off
	global_store_dwordx2 v[252:253], v[208:209], off
	s_waitcnt vmcnt(8)
	v_pk_fma_f32 v[124:125], v[140:141], v[124:125], v[212:213]
	v_pk_fma_f32 v[126:127], v[142:143], v[126:127], v[214:215]
	v_pk_mul_f32 v[212:213], v[206:207], v[124:125] op_sel:[1,0]
	v_pk_mul_f32 v[214:215], v[206:207], v[126:127] op_sel:[1,0]
	v_pk_mul_f32 v[212:213], v[152:153], v[212:213]
	v_pk_mul_f32 v[214:215], v[154:155], v[214:215]
	v_cvt_pk_bf16_f32 v212, v212, v213
	v_cvt_pk_bf16_f32 v213, v214, v215
	global_store_dwordx4 v[164:165], v[124:127], off offset:64
	global_store_dwordx2 v[252:253], v[212:213], off offset:32
	s_waitcnt vmcnt(9)
	v_pk_fma_f32 v[120:121], v[136:137], v[120:121], v[216:217]
	v_pk_fma_f32 v[122:123], v[138:139], v[122:123], v[218:219]
	v_pk_mul_f32 v[216:217], v[206:207], v[120:121] op_sel:[1,0]
	v_pk_mul_f32 v[218:219], v[206:207], v[122:123] op_sel:[1,0]
	v_pk_mul_f32 v[216:217], v[156:157], v[216:217]
	v_pk_mul_f32 v[218:219], v[158:159], v[218:219]
	v_cvt_pk_bf16_f32 v216, v216, v217
	v_cvt_pk_bf16_f32 v217, v218, v219
	global_store_dwordx4 v[164:165], v[120:123], off offset:512
	global_store_dwordx2 v[252:253], v[216:217], off offset:256
	s_waitcnt vmcnt(10)
	v_pk_fma_f32 v[116:117], v[132:133], v[116:117], v[220:221]
	v_pk_fma_f32 v[118:119], v[134:135], v[118:119], v[222:223]
	v_pk_mul_f32 v[220:221], v[206:207], v[116:117] op_sel:[1,0]
	v_pk_mul_f32 v[222:223], v[206:207], v[118:119] op_sel:[1,0]
	v_pk_mul_f32 v[220:221], v[160:161], v[220:221]
	v_pk_mul_f32 v[222:223], v[162:163], v[222:223]
	v_cvt_pk_bf16_f32 v220, v220, v221
	v_cvt_pk_bf16_f32 v221, v222, v223
	global_store_dwordx4 v[164:165], v[116:119], off offset:576
	global_store_dwordx2 v[252:253], v[220:221], off offset:288
	global_load_dwordx4 v[208:211], v[172:173], off
	global_load_dwordx4 v[212:215], v[172:173], off offset:64
	global_load_dwordx4 v[216:219], v[172:173], off offset:512
	global_load_dwordx4 v[220:223], v[172:173], off offset:576
	ds_read_b64 v[206:207], v33 offset:16512
	v_lshlrev_b64 v[252:253], 10, v[170:171]
	v_lshl_add_u64 v[252:253], v[252:253], 0, v[34:35]
	v_lshl_add_u64 v[252:253], v[252:253], 1, s[6:7]
	s_waitcnt lgkmcnt(0)
	v_pk_mul_f32 v[112:113], v[112:113], v[206:207] op_sel_hi:[1,0]
	v_pk_mul_f32 v[114:115], v[114:115], v[206:207] op_sel_hi:[1,0]
	v_pk_mul_f32 v[108:109], v[108:109], v[206:207] op_sel_hi:[1,0]
	v_pk_mul_f32 v[110:111], v[110:111], v[206:207] op_sel_hi:[1,0]
	v_pk_mul_f32 v[104:105], v[104:105], v[206:207] op_sel_hi:[1,0]
	v_pk_mul_f32 v[106:107], v[106:107], v[206:207] op_sel_hi:[1,0]
	v_pk_mul_f32 v[100:101], v[100:101], v[206:207] op_sel_hi:[1,0]
	v_pk_mul_f32 v[102:103], v[102:103], v[206:207] op_sel_hi:[1,0]
	s_waitcnt vmcnt(15)
	v_pk_fma_f32 v[112:113], v[144:145], v[112:113], v[224:225]
	v_pk_fma_f32 v[114:115], v[146:147], v[114:115], v[226:227]
	v_pk_mul_f32 v[224:225], v[206:207], v[112:113] op_sel:[1,0]
	v_pk_mul_f32 v[226:227], v[206:207], v[114:115] op_sel:[1,0]
	v_pk_mul_f32 v[224:225], v[148:149], v[224:225]
	v_pk_mul_f32 v[226:227], v[150:151], v[226:227]
	v_cvt_pk_bf16_f32 v224, v224, v225
	v_cvt_pk_bf16_f32 v225, v226, v227
	global_store_dwordx4 v[168:169], v[112:115], off
	global_store_dwordx2 v[252:253], v[224:225], off
	s_waitcnt vmcnt(16)
; __device__ __forceinline__ unsigned cvt_pk_bf16(float lo, float hi) { unsigned r; asm volatile("v_cvt_pk_bf16_f32 %0, %1, %2" : "=v"(r) : "v"(lo), "v"(hi)); return r; }
;     __device__ __forceinline__ void fused(f32x4 (&acc)[2][2][4][2], const Unit& u, int wr, int wc, int fr, int fq, PG8_LAS unsigned char* lds, int wid, int lane) const {
;     ...
; #pragma unroll
;         for (int ai = 0; ai < 2; ++ai)
; #pragma unroll
;             for (int m = 0; m < 4; ++m) { const int r = ai * HALF + wr * 64 + m * 16 + fr; const f32x2v sr = S[r]; const size_t off = (size_t)(u.pm * BM + r) * 1024 + col0;
; #pragma unroll
;                 for (int bj = 0; bj < 2; ++bj)
; #pragma unroll
;                     for (int n = 0; n < 2; ++n) { const f32x4 bs = *(const f32x4*)(base + off + bj * HALF + n * 16); const f32x4 x1 = bs + acc[ai][bj][m][n] * sr.x * gv[bj][n];
;                         const f32x4 o = x1 * sr.y * g2v[bj][n]; u32x2 w; w.x = cvt_pk_bf16(o[0], o[1]); w.y = cvt_pk_bf16(o[2], o[3]);
;                         if (!dry || x1[0] == 1.2345e38f) { *(f32x4*)(out + off + bj * HALF + n * 16) = x1; *(u32x2*)(xn + off + bj * HALF + n * 16) = w; } }
;                 if (m & 1) asm volatile("" ::: "memory"); }
	v_pk_fma_f32 v[108:109], v[140:141], v[108:109], v[238:239]
	v_pk_fma_f32 v[110:111], v[142:143], v[110:111], v[240:241]
	v_pk_mul_f32 v[238:239], v[206:207], v[108:109] op_sel:[1,0]
	v_pk_mul_f32 v[240:241], v[206:207], v[110:111] op_sel:[1,0]
	v_pk_mul_f32 v[238:239], v[152:153], v[238:239]
	v_pk_mul_f32 v[240:241], v[154:155], v[240:241]
	v_cvt_pk_bf16_f32 v238, v238, v239
	v_cvt_pk_bf16_f32 v239, v240, v241
	global_store_dwordx4 v[168:169], v[108:111], off offset:64
	global_store_dwordx2 v[252:253], v[238:239], off offset:32
	s_waitcnt vmcnt(17)
	v_pk_fma_f32 v[104:105], v[136:137], v[104:105], v[242:243]
	v_pk_fma_f32 v[106:107], v[138:139], v[106:107], v[244:245]
	v_pk_mul_f32 v[242:243], v[206:207], v[104:105] op_sel:[1,0]
	v_pk_mul_f32 v[244:245], v[206:207], v[106:107] op_sel:[1,0]
	v_pk_mul_f32 v[242:243], v[156:157], v[242:243]
	v_pk_mul_f32 v[244:245], v[158:159], v[244:245]
	v_cvt_pk_bf16_f32 v242, v242, v243
	v_cvt_pk_bf16_f32 v243, v244, v245
	global_store_dwordx4 v[168:169], v[104:107], off offset:512
	global_store_dwordx2 v[252:253], v[242:243], off offset:256
	s_waitcnt vmcnt(18)
	v_pk_fma_f32 v[100:101], v[132:133], v[100:101], v[246:247]
	v_pk_fma_f32 v[102:103], v[134:135], v[102:103], v[248:249]
	v_pk_mul_f32 v[246:247], v[206:207], v[100:101] op_sel:[1,0]
	v_pk_mul_f32 v[248:249], v[206:207], v[102:103] op_sel:[1,0]
	v_pk_mul_f32 v[246:247], v[160:161], v[246:247]
	v_pk_mul_f32 v[248:249], v[162:163], v[248:249]
	v_cvt_pk_bf16_f32 v246, v246, v247
	v_cvt_pk_bf16_f32 v247, v248, v249
	global_store_dwordx4 v[168:169], v[100:103], off offset:576
	global_store_dwordx2 v[252:253], v[246:247], off offset:288
	global_load_dwordx4 v[224:227], v[176:177], off
	global_load_dwordx4 v[238:241], v[176:177], off offset:64
	global_load_dwordx4 v[242:245], v[176:177], off offset:512
	global_load_dwordx4 v[246:249], v[176:177], off offset:576
	ds_read_b64 v[206:207], v33 offset:16640
	v_lshlrev_b64 v[252:253], 10, v[174:175]
	v_lshl_add_u64 v[252:253], v[252:253], 0, v[34:35]
	v_lshl_add_u64 v[252:253], v[252:253], 1, s[6:7]
	s_waitcnt lgkmcnt(0)
	v_pk_mul_f32 v[96:97], v[96:97], v[206:207] op_sel_hi:[1,0]
	v_pk_mul_f32 v[98:99], v[98:99], v[206:207] op_sel_hi:[1,0]
	v_pk_mul_f32 v[92:93], v[92:93], v[206:207] op_sel_hi:[1,0]
	v_pk_mul_f32 v[94:95], v[94:95], v[206:207] op_sel_hi:[1,0]
	v_pk_mul_f32 v[88:89], v[88:89], v[206:207] op_sel_hi:[1,0]
	v_pk_mul_f32 v[90:91], v[90:91], v[206:207] op_sel_hi:[1,0]
	v_pk_mul_f32 v[84:85], v[84:85], v[206:207] op_sel_hi:[1,0]
	v_pk_mul_f32 v[86:87], v[86:87], v[206:207] op_sel_hi:[1,0]
	s_waitcnt vmcnt(15)
	v_pk_fma_f32 v[96:97], v[144:145], v[96:97], v[208:209]
	v_pk_fma_f32 v[98:99], v[146:147], v[98:99], v[210:211]
	v_pk_mul_f32 v[208:209], v[206:207], v[96:97] op_sel:[1,0]
	v_pk_mul_f32 v[210:211], v[206:207], v[98:99] op_sel:[1,0]
	v_pk_mul_f32 v[208:209], v[148:149], v[208:209]
	v_pk_mul_f32 v[210:211], v[150:151], v[210:211]
	v_cvt_pk_bf16_f32 v208, v208, v209
	v_cvt_pk_bf16_f32 v209, v210, v211
	global_store_dwordx4 v[172:173], v[96:99], off
	global_store_dwordx2 v[252:253], v[208:209], off
	s_waitcnt vmcnt(16)
	v_pk_fma_f32 v[92:93], v[140:141], v[92:93], v[212:213]
	v_pk_fma_f32 v[94:95], v[142:143], v[94:95], v[214:215]
	v_pk_mul_f32 v[212:213], v[206:207], v[92:93] op_sel:[1,0]
	v_pk_mul_f32 v[214:215], v[206:207], v[94:95] op_sel:[1,0]
	v_pk_mul_f32 v[212:213], v[152:153], v[212:213]
	v_pk_mul_f32 v[214:215], v[154:155], v[214:215]
	v_cvt_pk_bf16_f32 v212, v212, v213
	v_cvt_pk_bf16_f32 v213, v214, v215
	global_store_dwordx4 v[172:173], v[92:95], off offset:64
	global_store_dwordx2 v[252:253], v[212:213], off offset:32
	s_waitcnt vmcnt(17)
	v_pk_fma_f32 v[88:89], v[136:137], v[88:89], v[216:217]
	v_pk_fma_f32 v[90:91], v[138:139], v[90:91], v[218:219]
	v_pk_mul_f32 v[216:217], v[206:207], v[88:89] op_sel:[1,0]
	v_pk_mul_f32 v[218:219], v[206:207], v[90:91] op_sel:[1,0]
	v_pk_mul_f32 v[216:217], v[156:157], v[216:217]
	v_pk_mul_f32 v[218:219], v[158:159], v[218:219]
	v_cvt_pk_bf16_f32 v216, v216, v217
	v_cvt_pk_bf16_f32 v217, v218, v219
	global_store_dwordx4 v[172:173], v[88:91], off offset:512
	global_store_dwordx2 v[252:253], v[216:217], off offset:256
	s_waitcnt vmcnt(18)
	v_pk_fma_f32 v[84:85], v[132:133], v[84:85], v[220:221]
	v_pk_fma_f32 v[86:87], v[134:135], v[86:87], v[222:223]
	v_pk_mul_f32 v[220:221], v[206:207], v[84:85] op_sel:[1,0]
	v_pk_mul_f32 v[222:223], v[206:207], v[86:87] op_sel:[1,0]
	v_pk_mul_f32 v[220:221], v[160:161], v[220:221]
	v_pk_mul_f32 v[222:223], v[162:163], v[222:223]
	v_cvt_pk_bf16_f32 v220, v220, v221
	v_cvt_pk_bf16_f32 v221, v222, v223
	global_store_dwordx4 v[172:173], v[84:87], off offset:576
	global_store_dwordx2 v[252:253], v[220:221], off offset:288
	global_load_dwordx4 v[208:211], v[180:181], off
	global_load_dwordx4 v[212:215], v[180:181], off offset:64
	global_load_dwordx4 v[216:219], v[180:181], off offset:512
	global_load_dwordx4 v[220:223], v[180:181], off offset:576
	ds_read_b64 v[206:207], v33 offset:16768
	v_lshlrev_b64 v[252:253], 10, v[178:179]
	v_lshl_add_u64 v[252:253], v[252:253], 0, v[34:35]
	v_lshl_add_u64 v[252:253], v[252:253], 1, s[6:7]
	s_waitcnt lgkmcnt(0)
	v_pk_mul_f32 v[80:81], v[80:81], v[206:207] op_sel_hi:[1,0]
	v_pk_mul_f32 v[82:83], v[82:83], v[206:207] op_sel_hi:[1,0]
	v_pk_mul_f32 v[76:77], v[76:77], v[206:207] op_sel_hi:[1,0]
	v_pk_mul_f32 v[78:79], v[78:79], v[206:207] op_sel_hi:[1,0]
	v_pk_mul_f32 v[72:73], v[72:73], v[206:207] op_sel_hi:[1,0]
	v_pk_mul_f32 v[74:75], v[74:75], v[206:207] op_sel_hi:[1,0]
	v_pk_mul_f32 v[68:69], v[68:69], v[206:207] op_sel_hi:[1,0]
	v_pk_mul_f32 v[70:71], v[70:71], v[206:207] op_sel_hi:[1,0]
	s_waitcnt vmcnt(15)
; __device__ __forceinline__ unsigned cvt_pk_bf16(float lo, float hi) { unsigned r; asm volatile("v_cvt_pk_bf16_f32 %0, %1, %2" : "=v"(r) : "v"(lo), "v"(hi)); return r; }
;     __device__ __forceinline__ void fused(f32x4 (&acc)[2][2][4][2], const Unit& u, int wr, int wc, int fr, int fq, PG8_LAS unsigned char* lds, int wid, int lane) const {
;     ...
; #pragma unroll
;         for (int ai = 0; ai < 2; ++ai)
; #pragma unroll
;             for (int m = 0; m < 4; ++m) { const int r = ai * HALF + wr * 64 + m * 16 + fr; const f32x2v sr = S[r]; const size_t off = (size_t)(u.pm * BM + r) * 1024 + col0;
; #pragma unroll
;                 for (int bj = 0; bj < 2; ++bj)
; #pragma unroll
;                     for (int n = 0; n < 2; ++n) { const f32x4 bs = *(const f32x4*)(base + off + bj * HALF + n * 16); const f32x4 x1 = bs + acc[ai][bj][m][n] * sr.x * gv[bj][n];
;                         const f32x4 o = x1 * sr.y * g2v[bj][n]; u32x2 w; w.x = cvt_pk_bf16(o[0], o[1]); w.y = cvt_pk_bf16(o[2], o[3]);
;                         if (!dry || x1[0] == 1.2345e38f) { *(f32x4*)(out + off + bj * HALF + n * 16) = x1; *(u32x2*)(xn + off + bj * HALF + n * 16) = w; } }
;                 if (m & 1) asm volatile("" ::: "memory"); }
	v_pk_fma_f32 v[80:81], v[144:145], v[80:81], v[224:225]
	v_pk_fma_f32 v[82:83], v[146:147], v[82:83], v[226:227]
	v_pk_mul_f32 v[224:225], v[206:207], v[80:81] op_sel:[1,0]
	v_pk_mul_f32 v[226:227], v[206:207], v[82:83] op_sel:[1,0]
	v_pk_mul_f32 v[224:225], v[148:149], v[224:225]
	v_pk_mul_f32 v[226:227], v[150:151], v[226:227]
	v_cvt_pk_bf16_f32 v224, v224, v225
	v_cvt_pk_bf16_f32 v225, v226, v227
	global_store_dwordx4 v[176:177], v[80:83], off
	global_store_dwordx2 v[252:253], v[224:225], off
	s_waitcnt vmcnt(16)
	v_pk_fma_f32 v[76:77], v[140:141], v[76:77], v[238:239]
	v_pk_fma_f32 v[78:79], v[142:143], v[78:79], v[240:241]
	v_pk_mul_f32 v[238:239], v[206:207], v[76:77] op_sel:[1,0]
	v_pk_mul_f32 v[240:241], v[206:207], v[78:79] op_sel:[1,0]
	v_pk_mul_f32 v[238:239], v[152:153], v[238:239]
	v_pk_mul_f32 v[240:241], v[154:155], v[240:241]
	v_cvt_pk_bf16_f32 v238, v238, v239
	v_cvt_pk_bf16_f32 v239, v240, v241
	global_store_dwordx4 v[176:177], v[76:79], off offset:64
	global_store_dwordx2 v[252:253], v[238:239], off offset:32
	s_waitcnt vmcnt(17)
	v_pk_fma_f32 v[72:73], v[136:137], v[72:73], v[242:243]
	v_pk_fma_f32 v[74:75], v[138:139], v[74:75], v[244:245]
	v_pk_mul_f32 v[242:243], v[206:207], v[72:73] op_sel:[1,0]
	v_pk_mul_f32 v[244:245], v[206:207], v[74:75] op_sel:[1,0]
	v_pk_mul_f32 v[242:243], v[156:157], v[242:243]
	v_pk_mul_f32 v[244:245], v[158:159], v[244:245]
	v_cvt_pk_bf16_f32 v242, v242, v243
	v_cvt_pk_bf16_f32 v243, v244, v245
	global_store_dwordx4 v[176:177], v[72:75], off offset:512
	global_store_dwordx2 v[252:253], v[242:243], off offset:256
	s_waitcnt vmcnt(18)
	v_pk_fma_f32 v[68:69], v[132:133], v[68:69], v[246:247]
	v_pk_fma_f32 v[70:71], v[134:135], v[70:71], v[248:249]
	v_pk_mul_f32 v[246:247], v[206:207], v[68:69] op_sel:[1,0]
	v_pk_mul_f32 v[248:249], v[206:207], v[70:71] op_sel:[1,0]
	v_pk_mul_f32 v[246:247], v[160:161], v[246:247]
	v_pk_mul_f32 v[248:249], v[162:163], v[248:249]
	v_cvt_pk_bf16_f32 v246, v246, v247
	v_cvt_pk_bf16_f32 v247, v248, v249
	global_store_dwordx4 v[176:177], v[68:71], off offset:576
	global_store_dwordx2 v[252:253], v[246:247], off offset:288
	global_load_dwordx4 v[224:227], v[184:185], off
	global_load_dwordx4 v[238:241], v[184:185], off offset:64
	global_load_dwordx4 v[242:245], v[184:185], off offset:512
	global_load_dwordx4 v[246:249], v[184:185], off offset:576
	ds_read_b64 v[206:207], v33 offset:17408
	v_lshlrev_b64 v[252:253], 10, v[182:183]
	v_lshl_add_u64 v[252:253], v[252:253], 0, v[34:35]
	v_lshl_add_u64 v[252:253], v[252:253], 1, s[6:7]
	s_waitcnt lgkmcnt(0)
	v_pk_mul_f32 v[64:65], v[64:65], v[206:207] op_sel_hi:[1,0]
	v_pk_mul_f32 v[66:67], v[66:67], v[206:207] op_sel_hi:[1,0]
	v_pk_mul_f32 v[60:61], v[60:61], v[206:207] op_sel_hi:[1,0]
	v_pk_mul_f32 v[62:63], v[62:63], v[206:207] op_sel_hi:[1,0]
	v_pk_mul_f32 v[56:57], v[56:57], v[206:207] op_sel_hi:[1,0]
	v_pk_mul_f32 v[58:59], v[58:59], v[206:207] op_sel_hi:[1,0]
	v_pk_mul_f32 v[52:53], v[52:53], v[206:207] op_sel_hi:[1,0]
	v_pk_mul_f32 v[54:55], v[54:55], v[206:207] op_sel_hi:[1,0]
	s_waitcnt vmcnt(15)
	v_pk_fma_f32 v[64:65], v[144:145], v[64:65], v[208:209]
	v_pk_fma_f32 v[66:67], v[146:147], v[66:67], v[210:211]
	v_pk_mul_f32 v[208:209], v[206:207], v[64:65] op_sel:[1,0]
	v_pk_mul_f32 v[210:211], v[206:207], v[66:67] op_sel:[1,0]
	v_pk_mul_f32 v[208:209], v[148:149], v[208:209]
	v_pk_mul_f32 v[210:211], v[150:151], v[210:211]
	v_cvt_pk_bf16_f32 v208, v208, v209
	v_cvt_pk_bf16_f32 v209, v210, v211
	global_store_dwordx4 v[180:181], v[64:67], off
	global_store_dwordx2 v[252:253], v[208:209], off
	s_waitcnt vmcnt(16)
	v_pk_fma_f32 v[60:61], v[140:141], v[60:61], v[212:213]
	v_pk_fma_f32 v[62:63], v[142:143], v[62:63], v[214:215]
	v_pk_mul_f32 v[212:213], v[206:207], v[60:61] op_sel:[1,0]
	v_pk_mul_f32 v[214:215], v[206:207], v[62:63] op_sel:[1,0]
	v_pk_mul_f32 v[212:213], v[152:153], v[212:213]
	v_pk_mul_f32 v[214:215], v[154:155], v[214:215]
	v_cvt_pk_bf16_f32 v212, v212, v213
	v_cvt_pk_bf16_f32 v213, v214, v215
	global_store_dwordx4 v[180:181], v[60:63], off offset:64
	global_store_dwordx2 v[252:253], v[212:213], off offset:32
	s_waitcnt vmcnt(17)
	v_pk_fma_f32 v[56:57], v[136:137], v[56:57], v[216:217]
	v_pk_fma_f32 v[58:59], v[138:139], v[58:59], v[218:219]
	v_pk_mul_f32 v[216:217], v[206:207], v[56:57] op_sel:[1,0]
	v_pk_mul_f32 v[218:219], v[206:207], v[58:59] op_sel:[1,0]
	v_pk_mul_f32 v[216:217], v[156:157], v[216:217]
	v_pk_mul_f32 v[218:219], v[158:159], v[218:219]
	v_cvt_pk_bf16_f32 v216, v216, v217
	v_cvt_pk_bf16_f32 v217, v218, v219
	global_store_dwordx4 v[180:181], v[56:59], off offset:512
	global_store_dwordx2 v[252:253], v[216:217], off offset:256
	s_waitcnt vmcnt(18)
	v_pk_fma_f32 v[52:53], v[132:133], v[52:53], v[220:221]
	v_pk_fma_f32 v[54:55], v[134:135], v[54:55], v[222:223]
	v_pk_mul_f32 v[220:221], v[206:207], v[52:53] op_sel:[1,0]
	v_pk_mul_f32 v[222:223], v[206:207], v[54:55] op_sel:[1,0]
	v_pk_mul_f32 v[220:221], v[160:161], v[220:221]
	v_pk_mul_f32 v[222:223], v[162:163], v[222:223]
	v_cvt_pk_bf16_f32 v220, v220, v221
	v_cvt_pk_bf16_f32 v221, v222, v223
	global_store_dwordx4 v[180:181], v[52:55], off offset:576
	global_store_dwordx2 v[252:253], v[220:221], off offset:288
	global_load_dwordx4 v[208:211], v[188:189], off
	global_load_dwordx4 v[212:215], v[188:189], off offset:64
	global_load_dwordx4 v[216:219], v[188:189], off offset:512
	global_load_dwordx4 v[220:223], v[188:189], off offset:576
	ds_read_b64 v[206:207], v33 offset:17536
	v_lshlrev_b64 v[252:253], 10, v[186:187]
	v_lshl_add_u64 v[252:253], v[252:253], 0, v[34:35]
	v_lshl_add_u64 v[252:253], v[252:253], 1, s[6:7]
	s_waitcnt lgkmcnt(0)
; __device__ __forceinline__ unsigned cvt_pk_bf16(float lo, float hi) { unsigned r; asm volatile("v_cvt_pk_bf16_f32 %0, %1, %2" : "=v"(r) : "v"(lo), "v"(hi)); return r; }
;     __device__ __forceinline__ void fused(f32x4 (&acc)[2][2][4][2], const Unit& u, int wr, int wc, int fr, int fq, PG8_LAS unsigned char* lds, int wid, int lane) const {
;     ...
; #pragma unroll
;         for (int ai = 0; ai < 2; ++ai)
; #pragma unroll
;             for (int m = 0; m < 4; ++m) { const int r = ai * HALF + wr * 64 + m * 16 + fr; const f32x2v sr = S[r]; const size_t off = (size_t)(u.pm * BM + r) * 1024 + col0;
; #pragma unroll
;                 for (int bj = 0; bj < 2; ++bj)
; #pragma unroll
;                     for (int n = 0; n < 2; ++n) { const f32x4 bs = *(const f32x4*)(base + off + bj * HALF + n * 16); const f32x4 x1 = bs + acc[ai][bj][m][n] * sr.x * gv[bj][n];
;                         const f32x4 o = x1 * sr.y * g2v[bj][n]; u32x2 w; w.x = cvt_pk_bf16(o[0], o[1]); w.y = cvt_pk_bf16(o[2], o[3]);
;                         if (!dry || x1[0] == 1.2345e38f) { *(f32x4*)(out + off + bj * HALF + n * 16) = x1; *(u32x2*)(xn + off + bj * HALF + n * 16) = w; } }
;                 if (m & 1) asm volatile("" ::: "memory"); }
	v_pk_mul_f32 v[48:49], v[48:49], v[206:207] op_sel_hi:[1,0]
	v_pk_mul_f32 v[50:51], v[50:51], v[206:207] op_sel_hi:[1,0]
	v_pk_mul_f32 v[44:45], v[44:45], v[206:207] op_sel_hi:[1,0]
	v_pk_mul_f32 v[46:47], v[46:47], v[206:207] op_sel_hi:[1,0]
	v_pk_mul_f32 v[40:41], v[40:41], v[206:207] op_sel_hi:[1,0]
	v_pk_mul_f32 v[42:43], v[42:43], v[206:207] op_sel_hi:[1,0]
	v_pk_mul_f32 v[36:37], v[36:37], v[206:207] op_sel_hi:[1,0]
	v_pk_mul_f32 v[38:39], v[38:39], v[206:207] op_sel_hi:[1,0]
	s_waitcnt vmcnt(15)
	v_pk_fma_f32 v[48:49], v[144:145], v[48:49], v[224:225]
	v_pk_fma_f32 v[50:51], v[146:147], v[50:51], v[226:227]
	v_pk_mul_f32 v[224:225], v[206:207], v[48:49] op_sel:[1,0]
	v_pk_mul_f32 v[226:227], v[206:207], v[50:51] op_sel:[1,0]
	v_pk_mul_f32 v[224:225], v[148:149], v[224:225]
	v_pk_mul_f32 v[226:227], v[150:151], v[226:227]
	v_cvt_pk_bf16_f32 v224, v224, v225
	v_cvt_pk_bf16_f32 v225, v226, v227
	global_store_dwordx4 v[184:185], v[48:51], off
	global_store_dwordx2 v[252:253], v[224:225], off
	s_waitcnt vmcnt(16)
	v_pk_fma_f32 v[44:45], v[140:141], v[44:45], v[238:239]
	v_pk_fma_f32 v[46:47], v[142:143], v[46:47], v[240:241]
	v_pk_mul_f32 v[238:239], v[206:207], v[44:45] op_sel:[1,0]
	v_pk_mul_f32 v[240:241], v[206:207], v[46:47] op_sel:[1,0]
	v_pk_mul_f32 v[238:239], v[152:153], v[238:239]
	v_pk_mul_f32 v[240:241], v[154:155], v[240:241]
	v_cvt_pk_bf16_f32 v238, v238, v239
	v_cvt_pk_bf16_f32 v239, v240, v241
	global_store_dwordx4 v[184:185], v[44:47], off offset:64
	global_store_dwordx2 v[252:253], v[238:239], off offset:32
	s_waitcnt vmcnt(17)
	v_pk_fma_f32 v[40:41], v[136:137], v[40:41], v[242:243]
	v_pk_fma_f32 v[42:43], v[138:139], v[42:43], v[244:245]
	v_pk_mul_f32 v[242:243], v[206:207], v[40:41] op_sel:[1,0]
	v_pk_mul_f32 v[244:245], v[206:207], v[42:43] op_sel:[1,0]
	v_pk_mul_f32 v[242:243], v[156:157], v[242:243]
	v_pk_mul_f32 v[244:245], v[158:159], v[244:245]
	v_cvt_pk_bf16_f32 v242, v242, v243
	v_cvt_pk_bf16_f32 v243, v244, v245
	global_store_dwordx4 v[184:185], v[40:43], off offset:512
	global_store_dwordx2 v[252:253], v[242:243], off offset:256
	s_waitcnt vmcnt(18)
	v_pk_fma_f32 v[36:37], v[132:133], v[36:37], v[246:247]
	v_pk_fma_f32 v[38:39], v[134:135], v[38:39], v[248:249]
	v_pk_mul_f32 v[246:247], v[206:207], v[36:37] op_sel:[1,0]
	v_pk_mul_f32 v[248:249], v[206:207], v[38:39] op_sel:[1,0]
	v_pk_mul_f32 v[246:247], v[160:161], v[246:247]
	v_pk_mul_f32 v[248:249], v[162:163], v[248:249]
	v_cvt_pk_bf16_f32 v246, v246, v247
	v_cvt_pk_bf16_f32 v247, v248, v249
	global_store_dwordx4 v[184:185], v[36:39], off offset:576
	global_store_dwordx2 v[252:253], v[246:247], off offset:288
	global_load_dwordx4 v[224:227], v[192:193], off
	global_load_dwordx4 v[238:241], v[192:193], off offset:64
	global_load_dwordx4 v[242:245], v[192:193], off offset:512
	global_load_dwordx4 v[246:249], v[192:193], off offset:576
	ds_read_b64 v[206:207], v33 offset:17664
	v_lshlrev_b64 v[252:253], 10, v[190:191]
	v_lshl_add_u64 v[252:253], v[252:253], 0, v[34:35]
	v_lshl_add_u64 v[252:253], v[252:253], 1, s[6:7]
	s_waitcnt lgkmcnt(0)
	v_pk_mul_f32 v[28:29], v[28:29], v[206:207] op_sel_hi:[1,0]
	v_pk_mul_f32 v[30:31], v[30:31], v[206:207] op_sel_hi:[1,0]
	v_pk_mul_f32 v[24:25], v[24:25], v[206:207] op_sel_hi:[1,0]
	v_pk_mul_f32 v[26:27], v[26:27], v[206:207] op_sel_hi:[1,0]
	v_pk_mul_f32 v[20:21], v[20:21], v[206:207] op_sel_hi:[1,0]
	v_pk_mul_f32 v[22:23], v[22:23], v[206:207] op_sel_hi:[1,0]
	v_pk_mul_f32 v[16:17], v[16:17], v[206:207] op_sel_hi:[1,0]
	v_pk_mul_f32 v[18:19], v[18:19], v[206:207] op_sel_hi:[1,0]
	s_waitcnt vmcnt(15)
	v_pk_fma_f32 v[28:29], v[144:145], v[28:29], v[208:209]
	v_pk_fma_f32 v[30:31], v[146:147], v[30:31], v[210:211]
	v_pk_mul_f32 v[208:209], v[206:207], v[28:29] op_sel:[1,0]
	v_pk_mul_f32 v[210:211], v[206:207], v[30:31] op_sel:[1,0]
	v_pk_mul_f32 v[208:209], v[148:149], v[208:209]
	v_pk_mul_f32 v[210:211], v[150:151], v[210:211]
	v_cvt_pk_bf16_f32 v208, v208, v209
	v_cvt_pk_bf16_f32 v209, v210, v211
	global_store_dwordx4 v[188:189], v[28:31], off
	global_store_dwordx2 v[252:253], v[208:209], off
	s_waitcnt vmcnt(16)
; __device__ __forceinline__ unsigned cvt_pk_bf16(float lo, float hi) { unsigned r; asm volatile("v_cvt_pk_bf16_f32 %0, %1, %2" : "=v"(r) : "v"(lo), "v"(hi)); return r; }
;     __device__ __forceinline__ void fused(f32x4 (&acc)[2][2][4][2], const Unit& u, int wr, int wc, int fr, int fq, PG8_LAS unsigned char* lds, int wid, int lane) const {
;     ...
;             for (int m = 0; m < 4; ++m) { const int r = ai * HALF + wr * 64 + m * 16 + fr; const f32x2v sr = S[r]; const size_t off = (size_t)(u.pm * BM + r) * 1024 + col0;
; #pragma unroll
;                 for (int bj = 0; bj < 2; ++bj)
; #pragma unroll
;                     for (int n = 0; n < 2; ++n) { const f32x4 bs = *(const f32x4*)(base + off + bj * HALF + n * 16); const f32x4 x1 = bs + acc[ai][bj][m][n] * sr.x * gv[bj][n];
;                         const f32x4 o = x1 * sr.y * g2v[bj][n]; u32x2 w; w.x = cvt_pk_bf16(o[0], o[1]); w.y = cvt_pk_bf16(o[2], o[3]);
;                         if (!dry || x1[0] == 1.2345e38f) { *(f32x4*)(out + off + bj * HALF + n * 16) = x1; *(u32x2*)(xn + off + bj * HALF + n * 16) = w; } }
	v_pk_fma_f32 v[24:25], v[140:141], v[24:25], v[212:213]
	v_pk_fma_f32 v[26:27], v[142:143], v[26:27], v[214:215]
	v_pk_mul_f32 v[212:213], v[206:207], v[24:25] op_sel:[1,0]
	v_pk_mul_f32 v[214:215], v[206:207], v[26:27] op_sel:[1,0]
	v_pk_mul_f32 v[212:213], v[152:153], v[212:213]
	v_pk_mul_f32 v[214:215], v[154:155], v[214:215]
	v_cvt_pk_bf16_f32 v212, v212, v213
	v_cvt_pk_bf16_f32 v213, v214, v215
	global_store_dwordx4 v[188:189], v[24:27], off offset:64
	global_store_dwordx2 v[252:253], v[212:213], off offset:32
	s_waitcnt vmcnt(17)
	v_pk_fma_f32 v[20:21], v[136:137], v[20:21], v[216:217]
	v_pk_fma_f32 v[22:23], v[138:139], v[22:23], v[218:219]
	v_pk_mul_f32 v[216:217], v[206:207], v[20:21] op_sel:[1,0]
	v_pk_mul_f32 v[218:219], v[206:207], v[22:23] op_sel:[1,0]
	v_pk_mul_f32 v[216:217], v[156:157], v[216:217]
	v_pk_mul_f32 v[218:219], v[158:159], v[218:219]
	v_cvt_pk_bf16_f32 v216, v216, v217
	v_cvt_pk_bf16_f32 v217, v218, v219
	global_store_dwordx4 v[188:189], v[20:23], off offset:512
	global_store_dwordx2 v[252:253], v[216:217], off offset:256
	s_waitcnt vmcnt(18)
	v_pk_fma_f32 v[16:17], v[132:133], v[16:17], v[220:221]
	v_pk_fma_f32 v[18:19], v[134:135], v[18:19], v[222:223]
	v_pk_mul_f32 v[220:221], v[206:207], v[16:17] op_sel:[1,0]
	v_pk_mul_f32 v[222:223], v[206:207], v[18:19] op_sel:[1,0]
	v_pk_mul_f32 v[220:221], v[160:161], v[220:221]
	v_pk_mul_f32 v[222:223], v[162:163], v[222:223]
	v_cvt_pk_bf16_f32 v220, v220, v221
	v_cvt_pk_bf16_f32 v221, v222, v223
	global_store_dwordx4 v[188:189], v[16:19], off offset:576
	global_store_dwordx2 v[252:253], v[220:221], off offset:288
	ds_read_b64 v[206:207], v33 offset:17792
	v_lshlrev_b64 v[252:253], 10, v[204:205]
	v_lshl_add_u64 v[252:253], v[252:253], 0, v[34:35]
	v_lshl_add_u64 v[252:253], v[252:253], 1, s[6:7]
	s_waitcnt lgkmcnt(0)
	v_pk_mul_f32 v[12:13], v[12:13], v[206:207] op_sel_hi:[1,0]
	v_pk_mul_f32 v[14:15], v[14:15], v[206:207] op_sel_hi:[1,0]
	v_pk_mul_f32 v[8:9], v[8:9], v[206:207] op_sel_hi:[1,0]
	v_pk_mul_f32 v[10:11], v[10:11], v[206:207] op_sel_hi:[1,0]
	v_pk_mul_f32 v[4:5], v[4:5], v[206:207] op_sel_hi:[1,0]
	v_pk_mul_f32 v[6:7], v[6:7], v[206:207] op_sel_hi:[1,0]
	v_pk_mul_f32 v[0:1], v[0:1], v[206:207] op_sel_hi:[1,0]
	v_pk_mul_f32 v[2:3], v[2:3], v[206:207] op_sel_hi:[1,0]
	s_waitcnt vmcnt(11)
	v_pk_fma_f32 v[12:13], v[144:145], v[12:13], v[224:225]
	v_pk_fma_f32 v[14:15], v[146:147], v[14:15], v[226:227]
	v_pk_mul_f32 v[224:225], v[206:207], v[12:13] op_sel:[1,0]
	v_pk_mul_f32 v[226:227], v[206:207], v[14:15] op_sel:[1,0]
	v_pk_mul_f32 v[224:225], v[148:149], v[224:225]
	v_pk_mul_f32 v[226:227], v[150:151], v[226:227]
	v_cvt_pk_bf16_f32 v224, v224, v225
	v_cvt_pk_bf16_f32 v225, v226, v227
	global_store_dwordx4 v[192:193], v[12:15], off
	global_store_dwordx2 v[252:253], v[224:225], off
	s_waitcnt vmcnt(12)
	v_pk_fma_f32 v[8:9], v[140:141], v[8:9], v[238:239]
	v_pk_fma_f32 v[10:11], v[142:143], v[10:11], v[240:241]
	v_pk_mul_f32 v[238:239], v[206:207], v[8:9] op_sel:[1,0]
	v_pk_mul_f32 v[240:241], v[206:207], v[10:11] op_sel:[1,0]
	v_pk_mul_f32 v[238:239], v[152:153], v[238:239]
	v_pk_mul_f32 v[240:241], v[154:155], v[240:241]
	v_cvt_pk_bf16_f32 v238, v238, v239
	v_cvt_pk_bf16_f32 v239, v240, v241
	global_store_dwordx4 v[192:193], v[8:11], off offset:64
	global_store_dwordx2 v[252:253], v[238:239], off offset:32
	s_waitcnt vmcnt(13)
	v_pk_fma_f32 v[4:5], v[136:137], v[4:5], v[242:243]
	v_pk_fma_f32 v[6:7], v[138:139], v[6:7], v[244:245]
	v_pk_mul_f32 v[242:243], v[206:207], v[4:5] op_sel:[1,0]
	v_pk_mul_f32 v[244:245], v[206:207], v[6:7] op_sel:[1,0]
	v_pk_mul_f32 v[242:243], v[156:157], v[242:243]
	v_pk_mul_f32 v[244:245], v[158:159], v[244:245]
	v_cvt_pk_bf16_f32 v242, v242, v243
	v_cvt_pk_bf16_f32 v243, v244, v245
	global_store_dwordx4 v[192:193], v[4:7], off offset:512
	global_store_dwordx2 v[252:253], v[242:243], off offset:256
	s_waitcnt vmcnt(14)
	v_pk_fma_f32 v[0:1], v[132:133], v[0:1], v[246:247]
	v_pk_fma_f32 v[2:3], v[134:135], v[2:3], v[248:249]
	v_pk_mul_f32 v[246:247], v[206:207], v[0:1] op_sel:[1,0]
	v_pk_mul_f32 v[248:249], v[206:207], v[2:3] op_sel:[1,0]
	v_pk_mul_f32 v[246:247], v[160:161], v[246:247]
	v_pk_mul_f32 v[248:249], v[162:163], v[248:249]
	v_cvt_pk_bf16_f32 v246, v246, v247
	v_cvt_pk_bf16_f32 v247, v248, v249
	global_store_dwordx4 v[192:193], v[0:3], off offset:576
	global_store_dwordx2 v[252:253], v[246:247], off offset:288
